# scan: panel-complete counter update deferred to the next iteration's vmcnt(0)+barrier (no dedicated wait for the o_a write-through stores)
# speedup vs baseline: 1.0083x; 1.0013x over previous
.LBB0_537:
	s_or_b64 exec, exec, s[0:1]
	s_and_b64 s[0:1], s[36:37], exec
	s_cselect_b32 s28, 16, 0x1000
	s_add_u32 s64, s76, 0x13d00000
	s_addc_u32 s65, s77, 0
	s_bfe_u32 s68, s96, 0x20006
	s_mul_i32 s0, s68, 0x3700
	s_add_i32 s71, s0, 0
	s_and_b32 s0, s96, 0xffffff00
	s_lshr_b32 s74, s96, 8
	s_add_i32 s84, s0, 0
	s_lshl_b32 s11, s74, 5
	s_add_i32 s80, s84, 0x12600
	s_cmpk_lt_u32 s96, 0x540
	v_readlane_b32 s20, v255, 31
	s_cselect_b64 s[40:41], -1, 0
	s_add_i32 s12, s20, -4
	s_lshl_b32 s13, s12, 2
	s_lshl_b32 s22, s12, 10
	s_cmpk_lt_u32 s96, 0x440
	s_cselect_b64 s[42:43], -1, 0
	s_lshl_b32 s66, s20, 10
	s_cmpk_lt_u32 s96, 0x340
	s_cselect_b64 s[46:47], -1, 0
	s_add_i32 s14, s20, 4
	s_lshl_b32 s15, s14, 2
	s_lshl_b32 s23, s14, 10
	s_cmpk_lt_u32 s96, 0x240
	s_cselect_b64 s[48:49], -1, 0
	s_add_i32 s16, s20, 8
	s_lshl_b32 s17, s16, 2
	s_lshl_b32 s24, s16, 10
	s_cmp_eq_u32 s20, 4
	s_cselect_b64 s[50:51], -1, 0
	s_cmp_eq_u32 s20, 2
	s_mov_b32 s0, 0xfc00000
	s_cselect_b32 s38, s0, 0x13d00000
	s_add_u32 s8, s76, s6
	s_addc_u32 s9, s77, 0
	s_mul_i32 s0, s20, 0x2400
	s_add_i32 s1, 0, 0x1a900
	s_add_i32 s81, s1, s0
	s_lshl_b32 s0, s74, 7
	s_add_i32 s83, s0, 0
	s_add_i32 s82, s81, 0x2000
	s_add_i32 s83, s83, 0x14800
	s_add_i32 s84, s84, 0x12400
	s_lshl_b32 s29, s20, 5
	s_add_u32 s6, s64, s6
	s_addc_u32 s7, s65, 0
	s_lshl_b32 s85, s33, 10
	s_add_u32 s18, s76, 0x10000
	v_writelane_b32 v255, s96, 33
	s_addc_u32 s19, s77, 0
	v_lshl_or_b32 v11, s68, 4, v9
	v_writelane_b32 v255, s18, 34
	v_add_u32_e32 v25, 1, v11
	v_lshlrev_b32_e32 v27, 3, v38
	v_writelane_b32 v255, s19, 35
	v_lshlrev_b32_e32 v10, 7, v25
	v_and_b32_e32 v22, 8, v27
	s_add_i32 s0, 0, 0x1cd00
	s_add_i32 s18, 0, 0x1f100
	v_add3_u32 v91, s1, v10, v22
	v_add3_u32 v92, s0, v10, v22
	v_add3_u32 v93, s18, v10, v22
	v_lshlrev_b32_e32 v10, 8, v25
	s_add_i32 s19, 0, 0x23900
	v_add3_u32 v28, s19, v10, v22
	v_lshlrev_b32_e32 v10, 7, v11
	v_add3_u32 v94, s1, v10, v22
	v_add3_u32 v95, s0, v10, v22
	v_add3_u32 v96, s18, v10, v22
	v_lshlrev_b32_e32 v10, 8, v11
	v_add3_u32 v29, s19, v10, v22
	v_add_u32_e32 v10, 1, v89
	s_add_i32 s19, 0, 0x21500
	v_lshl_add_u32 v32, v10, 7, s19
	v_xor_b32_e32 v10, v10, v39
	v_lshlrev_b32_e32 v10, 4, v10
	v_and_b32_e32 v33, 0x70, v10
	v_lshlrev_b32_e32 v10, 7, v89
	v_add_u32_e32 v34, s19, v10
	s_add_i32 s19, 0, 0x12800
	s_cmp_lg_u32 s12, 16
	v_add_u32_e32 v36, s19, v10
	v_or_b32_e32 v10, s13, v38
	s_cselect_b64 vcc, -1, 0
	v_xor_b32_e32 v22, v89, v39
	v_cndmask_b32_e32 v98, 64, v10, vcc
	v_bitop3_b32 v10, v38, v39, s13 bitop3:0x36
	v_lshlrev_b32_e32 v22, 4, v22
	v_and_or_b32 v10, v10, 7, v41
	v_and_b32_e32 v35, 0x70, v22
	v_lshlrev_b32_e32 v22, 4, v10
	v_mov_b32_e32 v10, 0
	v_mov_b32_e32 v23, v10
	s_cmp_lg_u32 s20, 16
	v_lshl_add_u64 v[48:49], s[4:5], 0, v[22:23]
	v_or_b32_e32 v22, s3, v38
	s_cselect_b64 vcc, -1, 0
	v_cndmask_b32_e32 v99, 64, v22, vcc
	v_bitop3_b32 v22, v38, v39, s3 bitop3:0x36
	v_and_or_b32 v22, v22, 7, v41
	v_lshlrev_b32_e32 v22, 4, v22
	s_cmp_lg_u32 s14, 16
	v_lshl_add_u64 v[50:51], s[4:5], 0, v[22:23]
	v_or_b32_e32 v22, s15, v38
	s_cselect_b64 vcc, -1, 0
	v_cndmask_b32_e32 v100, 64, v22, vcc
	v_bitop3_b32 v22, v38, v39, s15 bitop3:0x36
	v_and_or_b32 v22, v22, 7, v41
	v_lshlrev_b32_e32 v22, 4, v22
	s_cmp_lg_u32 s16, 16
	v_lshl_add_u64 v[52:53], s[4:5], 0, v[22:23]
	v_or_b32_e32 v22, s17, v38
	s_cselect_b64 vcc, -1, 0
	v_cndmask_b32_e32 v101, 64, v22, vcc
	v_bitop3_b32 v22, v38, v39, s17 bitop3:0x36
	v_and_or_b32 v22, v22, 7, v41
	v_lshlrev_b32_e32 v22, 4, v22
	v_lshl_add_u64 v[54:55], s[4:5], 0, v[22:23]
	v_xor_b32_e32 v22, v38, v20
	s_movk_i32 s10, 0x3700
	v_or_b32_e32 v22, v22, v41
	v_lshlrev_b32_e32 v41, 5, v9
	v_lshrrev_b32_e32 v45, 7, v42
	v_cmp_gt_u32_e64 s[0:1], 16, v40
	v_or_b32_e32 v103, v27, v41
	v_lshl_add_u32 v104, v40, 2, s71
	v_add_u32_e32 v40, s71, v41
	v_lshrrev_b32_e32 v41, 2, v9
	v_mul_lo_u32 v45, v45, s10
	v_or_b32_e32 v41, v90, v41
	v_add_u32_e32 v67, 0, v45
	v_bfe_u32 v45, v42, 3, 4
	v_mul_u32_u24_e32 v41, 0x48, v41
	v_and_b32_e32 v21, 12, v21
	v_mul_u32_u24_e32 v45, 0x48, v45
	v_or_b32_e32 v24, s11, v90
	v_add_lshl_u32 v105, v21, v41, 1
	v_lshl_or_b32 v21, v89, 6, v8
	v_add_lshl_u32 v8, v45, v8, 1
	v_mov_b32_e32 v45, v10
	v_and_b32_e32 v26, 7, v25
	v_lshl_add_u64 v[60:61], s[6:7], 0, v[44:45]
	v_cmp_eq_u32_e64 s[6:7], 0, v42
	v_lshrrev_b32_e32 v42, 3, v24
	v_and_b32_e32 v62, 8, v42
	v_bitop3_b32 v63, v42, v26, 5 bitop3:0x6c
	v_or_b32_e32 v63, v63, v62
	v_lshlrev_b32_e32 v68, 4, v63
	v_add_u32_e32 v63, 64, v24
	v_bitop3_b32 v45, v42, v25, 7 bitop3:0x78
	v_lshrrev_b32_e32 v64, 3, v63
	v_xor_b32_e32 v69, v42, v20
	v_bitop3_b32 v42, v42, v20, 5 bitop3:0x6c
	v_and_b32_e32 v65, 8, v64
	v_or_b32_e32 v42, v42, v62
	v_bitop3_b32 v62, v64, v20, 5 bitop3:0x6c
	v_or_b32_e32 v62, v62, v65
	v_lshlrev_b32_e32 v108, 4, v69
	v_lshlrev_b32_e32 v69, 4, v62
	v_or_b32_e32 v62, 16, v24
	v_lshlrev_b32_e32 v22, 4, v22
	v_lshlrev_b32_e32 v71, 1, v63
	v_lshrrev_b32_e32 v63, 3, v62
	v_lshl_add_u64 v[56:57], s[4:5], 0, v[22:23]
	v_xor_b32_e32 v22, v88, v20
	v_bitop3_b32 v26, v64, v26, 5 bitop3:0x6c
	v_bitop3_b32 v64, v63, v25, 7 bitop3:0x78
	v_lshlrev_b32_e32 v22, 4, v22
	v_or_b32_e32 v26, v26, v65
	v_lshlrev_b32_e32 v111, 4, v64
	v_and_b32_e32 v64, 8, v63
	v_bitop3_b32 v65, v63, v25, 7 bitop3:0x28
	s_movk_i32 s18, 0x48
	v_lshl_add_u64 v[58:59], s[8:9], 0, v[22:23]
	v_or_b32_e32 v23, s11, v9
	v_or_b32_e32 v65, v65, v64
	v_mul_u32_u24_e32 v30, 0x48, v11
	v_mul_u32_u24_e32 v31, 0x48, v9
	v_lshlrev_b32_e32 v97, 2, v11
	v_or_b32_e32 v22, 16, v90
	v_lshlrev_b32_e32 v72, 4, v65
	v_add_u32_e32 v65, 0x50, v24
	v_mul_lo_u32 v23, v23, s18
	v_mad_u32_u24 v11, v11, s18, 32
	v_lshlrev_b32_e32 v70, 1, v24
	v_add_lshl_u32 v109, v24, v30, 1
	v_add_lshl_u32 v110, v24, v31, 1
	v_lshrrev_b32_e32 v73, 3, v65
	v_xor_b32_e32 v75, v63, v20
	v_bitop3_b32 v63, v63, v20, 7 bitop3:0x6c
	v_add_lshl_u32 v113, v62, v30, 1
	v_add_lshl_u32 v115, v30, v90, 1
	v_add_lshl_u32 v116, v22, v30, 1
	v_add_u32_e32 v30, 0x480, v23
	v_add_lshl_u32 v119, v11, v90, 1
	v_add_lshl_u32 v120, v11, v22, 1
	v_or_b32_e32 v11, 32, v90
	v_lshlrev_b32_e32 v123, 2, v24
	v_or_b32_e32 v24, 1, v90
	v_cmp_eq_u32_e32 vcc, v90, v9
	v_lshlrev_b32_e32 v106, 5, v20
	v_and_b32_e32 v74, 8, v73
	v_bitop3_b32 v25, v73, v25, 7 bitop3:0x28
	v_or_b32_e32 v63, v63, v64
	v_bitop3_b32 v20, v73, v20, 7 bitop3:0x6c
	v_lshlrev_b32_e32 v73, 1, v62
	v_add_lshl_u32 v114, v62, v31, 1
	v_add_lshl_u32 v118, v30, v90, 1
	v_add_lshl_u32 v122, v11, v30, 1
	v_lshlrev_b32_e32 v124, 2, v62
	v_or_b32_e32 v30, 2, v90
	v_cndmask_b32_e64 v62, 0, 1.0, vcc
	v_cmp_eq_u32_e32 vcc, v24, v9
	v_lshlrev_b32_e32 v112, 4, v75
	v_lshlrev_b32_e32 v75, 4, v63
	v_add_lshl_u32 v117, v90, v23, 1
	v_add_lshl_u32 v121, v11, v23, 1
	v_add_lshl_u32 v125, v90, v31, 1
	v_add_lshl_u32 v23, v11, v31, 1
	v_or_b32_e32 v31, 3, v90
	v_cndmask_b32_e64 v63, 0, 1.0, vcc
	v_cmp_eq_u32_e32 vcc, v30, v9
	v_cmp_eq_u32_e64 s[4:5], 0, v9
	v_mad_u32_u24 v37, v9, s18, 16
	v_cmp_lt_u32_e64 s[8:9], v90, v9
	v_cmp_gt_u32_e64 s[10:11], v90, v9
	v_cmp_lt_u32_e64 s[12:13], v24, v9
	v_cmp_lt_u32_e64 s[14:15], v30, v9
	v_cmp_gt_u32_e64 s[16:17], v30, v9
	v_cmp_lt_u32_e64 s[18:19], v31, v9
	v_cmp_gt_u32_e64 s[20:21], v31, v9
	v_cndmask_b32_e64 v64, 0, 1.0, vcc
	v_cmp_eq_u32_e32 vcc, v31, v9
	v_lshlrev_b32_e32 v9, 2, v9
	v_lshl_add_u32 v24, v38, 10, s97
	s_mov_b32 s3, 0xdc00
	v_add3_u32 v126, v24, v9, s3
	v_and_b32_e32 v9, 3, v39
	s_movk_i32 s25, 0x2400
	v_lshlrev_b32_e32 v43, 2, v21
	v_lshlrev_b32_e32 v21, 1, v21
	v_lshl_or_b32 v9, v9, 3, s29
	v_lshlrev_b32_e32 v24, 1, v41
	s_waitcnt lgkmcnt(0)
	s_barrier
	v_lshlrev_b32_e32 v66, 2, v89
	v_or_b32_e32 v25, v25, v74
	v_or_b32_e32 v20, v20, v74
	v_add3_u32 v128, v9, v24, s25
	v_mov_b32_e32 v9, 0x3540
	v_add_u32_e32 v151, v67, v8
	v_add_u32_e32 v8, 0, v21
	s_mov_b32 s39, 0
	v_and_b32_e32 v102, 48, v39
	v_lshlrev_b32_e32 v26, 4, v26
	v_lshlrev_b32_e32 v42, 4, v42
	v_lshlrev_b32_e32 v25, 4, v25
	v_lshlrev_b32_e32 v20, 4, v20
	v_lshlrev_b32_e32 v74, 1, v65
	v_add_lshl_u32 v22, v37, v90, 1
	v_add_lshl_u32 v11, v11, v37, 1
	v_writelane_b32 v255, s97, 32
	v_lshl_or_b32 v129, v38, 4, v9
	s_add_i32 s3, 0, 0x15c00
	s_add_i32 s88, s22, 0
	s_add_i32 s89, s23, 0
	s_add_i32 s90, s24, 0
	v_add_u32_e32 v9, 0, v66
	v_add_u32_e32 v152, 0x12800, v8
	v_mbcnt_lo_u32_b32 v8, -1, 0
	s_mov_b64 s[52:53], s[38:39]
	v_add_u32_e32 v107, s70, v89
	v_lshlrev_b32_e32 v45, 4, v45
	v_cndmask_b32_e64 v65, 0, 1.0, vcc
	v_add_u32_e32 v127, 0x2d00, v103
	v_writelane_b32 v255, s29, 44
	v_or_b32_e32 v130, 0x3500, v102
	v_add_u32_e32 v131, v28, v68
	v_add_u32_e32 v132, v28, v26
	v_add_u32_e32 v133, v29, v42
	v_add_u32_e32 v134, v29, v69
	v_add_u32_e32 v135, s3, v70
	v_add_u32_e32 v136, s3, v71
	s_mov_b32 s86, 0x4038aa3b
	s_add_i32 s67, 0, 0x10000
	v_add_u32_e32 v137, v28, v72
	v_add_u32_e32 v138, v28, v25
	v_add_u32_e32 v139, v29, v75
	v_add_u32_e32 v140, v29, v20
	v_add_u32_e32 v141, s3, v73
	v_add_u32_e32 v142, s3, v74
	v_add_u32_e32 v143, v32, v33
	v_add_u32_e32 v145, v34, v35
	s_mov_b32 s87, 0xbfb8aa3b
	v_add_u32_e32 v146, v36, v44
	s_add_i32 s88, s88, 0x23900
	s_add_i32 s89, s89, 0x23900
	s_add_i32 s90, s90, 0x23900
	s_add_i32 s91, 0, 0x27900
	s_add_i32 s92, s81, 0x400
	s_add_i32 s93, s81, 0x800
	s_add_i32 s94, s81, 0xc00
	s_add_i32 s95, s81, 0x1400
	s_add_i32 s96, s81, 0x1800
	s_add_i32 s97, s81, 0x1c00
	s_add_i32 s3, 0, 0x16100
	s_add_i32 s69, 0, 0x18500
	v_mov_b32_e32 v147, 0xbf92477c
	v_add_u32_e32 v148, v40, v27
	s_xor_b64 s[54:55], s[26:27], -1
	v_add_u32_e32 v149, 0, v43
	v_add_u32_e32 v150, 0x12400, v9
	v_mov_b32_e32 v153, 0x3a27c5ac
	v_mbcnt_hi_u32_b32 v144, -1, v8
	v_add_u32_e32 v154, s71, v22
	v_add_u32_e32 v155, s71, v23
	v_add_u32_e32 v156, s71, v11
	s_mov_b32 s33, s28
	s_mov_b32 s29, 0
	v_add_u32_e32 v213, s67, v109
	v_add_u32_e32 v219, v93, v111
	v_add_u32_e32 v208, v94, v108
	v_add_u32_e32 v224, s71, v114
	v_add_u32_e32 v225, 0x15d80, v44
	v_xor_b32_e32 v243, 32, v144
	v_and_b32_e32 v241, 64, v144
	v_add_u32_e32 v21, 64, v241
	v_cmp_lt_i32_e32 vcc, v243, v21
	s_nop 1
	v_cndmask_b32_e32 v20, v144, v243, vcc
	v_lshlrev_b32_e32 v222, 2, v20
	v_add_u32_e32 v216, v94, v112
	v_add_u32_e32 v235, s3, v121
	v_add_u32_e32 v223, s67, v113
	v_add_u32_e32 v230, s69, v117
	v_xor_b32_e32 v242, 16, v144
	v_cmp_lt_i32_e32 vcc, v242, v21
	s_nop 1
	v_cndmask_b32_e32 v22, v144, v242, vcc
	v_lshlrev_b32_e32 v221, 2, v22
	v_add_u32_e32 v220, v91, v111
	v_or_b32_e32 v240, v102, v241
	v_add_u32_e32 v218, v96, v112
	v_add_u32_e32 v217, v95, v112
	v_add_u32_e32 v211, v93, v45
	v_add_u32_e32 v239, 0x12600, v97
	v_add_u32_e32 v209, v95, v108
	v_add_u32_e32 v210, v96, v108
	v_add_u32_e32 v227, s67, v115
	v_add_u32_e32 v233, s67, v119
	v_add_u32_e32 v237, s3, v122
	v_add_u32_e32 v226, s83, v102
	v_add_u32_e32 v214, s71, v110
	v_add_u32_e32 v212, v91, v45
	v_add_u32_e32 v234, s67, v120
	v_add_u32_e32 v236, s69, v121
	v_add_u32_e32 v229, s3, v117
	v_add_u32_e32 v232, s69, v118
	v_add_u32_e32 v215, v92, v111
	v_add_u32_e32 v238, s69, v122
	v_add_u32_e32 v228, s67, v116
	v_add_u32_e32 v207, v92, v45
	v_add_u32_e32 v231, s3, v118
	v_mov_b32_e32 v252, 0
	s_waitcnt vmcnt(0)

.LBB0_581:
	s_waitcnt vmcnt(0)
	s_waitcnt lgkmcnt(0)
	s_barrier
	v_cmp_ne_u32_e32 vcc, 0, v252
	s_cbranch_vccz .Lpub_none
	s_mov_b64 s[24:25], exec
	s_mov_b64 exec, vcc
	global_atomic_add v[250:251], v252, off
	s_mov_b64 exec, s[24:25]
	s_nop 1
	v_mov_b32_e32 v252, 0
.Lpub_none:
	s_and_saveexec_b64 s[24:25], s[22:23]
	s_cbranch_execz .LBB0_583
	ds_read_b128 v[20:23], v149 offset:56320
	s_waitcnt lgkmcnt(0)
	ds_read2st64_b32 v[8:9], v150 offset1:1
	ds_read_b128 v[24:27], v149 offset:56336
	s_add_i32 s22, 0, 0x14800
	ds_read_b128 v[28:31], v151 offset:9216
	ds_read_b128 v[32:35], v152
	v_add_f32_e32 v11, 0, v20
	s_waitcnt lgkmcnt(0)
	v_add_f32_e32 v8, v8, v9
	v_add_f32_e32 v9, v21, v11
	v_add_f32_e32 v9, v22, v9
	v_add_f32_e32 v9, v23, v9
	v_add_f32_e32 v9, v24, v9
	v_add_f32_e32 v9, v25, v9
	v_add_f32_e32 v9, v26, v9
	v_add_f32_e32 v9, v27, v9
	v_cvt_f32_f16_e32 v164, v28
	v_cvt_f32_f16_sdwa v165, v28 dst_sel:DWORD dst_unused:UNUSED_PAD src0_sel:WORD_1
	v_add_f32_dpp v9, v9, v9 quad_perm:[1,0,3,2] row_mask:0xf bank_mask:0xf bound_ctrl:1
	v_cvt_f32_f16_e32 v28, v29
	v_cvt_f32_f16_sdwa v29, v29 dst_sel:DWORD dst_unused:UNUSED_PAD src0_sel:WORD_1
	v_add_f32_dpp v9, v9, v9 quad_perm:[2,3,0,1] row_mask:0xf bank_mask:0xf bound_ctrl:1
	v_cvt_f32_f16_e32 v166, v32
	v_cvt_f32_f16_sdwa v167, v32 dst_sel:DWORD dst_unused:UNUSED_PAD src0_sel:WORD_1
	v_add_f32_dpp v9, v9, v9 row_half_mirror row_mask:0xf bank_mask:0xf bound_ctrl:1
	v_mul_f32_e32 v86, 0x3c800000, v9
	v_pk_add_f32 v[20:21], v[20:21], v[86:87] op_sel_hi:[1,0] neg_lo:[0,1] neg_hi:[0,1]
	v_add_u32_e32 v9, s22, v106
	v_pk_mul_f32 v[162:163], v[20:21], v[20:21]
	v_pk_add_f32 v[22:23], v[22:23], v[86:87] op_sel_hi:[1,0] neg_lo:[0,1] neg_hi:[0,1]
	ds_read_b128 v[36:39], v9 offset:2304
	ds_read_b128 v[40:43], v9 offset:2320
	ds_read_b128 v[82:85], v9 offset:2560
	ds_read_b128 v[158:161], v9 offset:2576
	v_pk_mul_f32 v[168:169], v[22:23], v[22:23]
	v_add_f32_e32 v9, v162, v163
	v_pk_add_f32 v[24:25], v[24:25], v[86:87] op_sel_hi:[1,0] neg_lo:[0,1] neg_hi:[0,1]
	v_add_f32_e32 v9, v168, v9
	v_pk_mul_f32 v[170:171], v[24:25], v[24:25]
	v_add_f32_e32 v9, v169, v9
	v_pk_add_f32 v[26:27], v[26:27], v[86:87] op_sel_hi:[1,0] neg_lo:[0,1] neg_hi:[0,1]
	v_add_f32_e32 v9, v170, v9
	v_pk_mul_f32 v[86:87], v[26:27], v[26:27]
	v_add_f32_e32 v9, v171, v9
	v_add_f32_e32 v9, v86, v9
	v_add_f32_e32 v9, v87, v9
	v_cvt_f32_f16_e32 v32, v33
	v_cvt_f32_f16_sdwa v33, v33 dst_sel:DWORD dst_unused:UNUSED_PAD src0_sel:WORD_1
	v_add_f32_dpp v9, v9, v9 quad_perm:[1,0,3,2] row_mask:0xf bank_mask:0xf bound_ctrl:1
	v_cvt_f32_f16_e32 v172, v30
	v_cvt_f32_f16_sdwa v173, v30 dst_sel:DWORD dst_unused:UNUSED_PAD src0_sel:WORD_1
	v_add_f32_dpp v9, v9, v9 quad_perm:[2,3,0,1] row_mask:0xf bank_mask:0xf bound_ctrl:1
	v_cvt_f32_f16_e32 v162, v34
	v_cvt_f32_f16_sdwa v163, v34 dst_sel:DWORD dst_unused:UNUSED_PAD src0_sel:WORD_1
	v_add_f32_dpp v9, v9, v9 row_half_mirror row_mask:0xf bank_mask:0xf bound_ctrl:1
	v_fmamk_f32 v9, v9, 0x3c800000, v153
	v_rsq_f32_e32 v86, v9
	s_nop 0
	v_pk_mul_f32 v[20:21], v[20:21], v[86:87] op_sel_hi:[1,0]
	v_pk_mul_f32 v[22:23], v[22:23], v[86:87] op_sel_hi:[1,0]
	s_waitcnt lgkmcnt(0)
	v_pk_fma_f32 v[20:21], v[36:37], v[20:21], v[82:83]
	v_pk_fma_f32 v[22:23], v[38:39], v[22:23], v[84:85]
	v_pk_fma_f32 v[20:21], v[8:9], v[164:165], v[20:21] op_sel_hi:[0,1,1]
	v_pk_fma_f32 v[22:23], v[8:9], v[28:29], v[22:23] op_sel_hi:[0,1,1]
	v_pk_mul_f32 v[20:21], v[20:21], v[166:167]
	v_pk_mul_f32 v[22:23], v[22:23], v[32:33]
	v_cvt_pk_f16_f32 v20, v20, v21
	v_cvt_pk_f16_f32 v21, v22, v23
	v_pk_mul_f32 v[22:23], v[24:25], v[86:87] op_sel_hi:[1,0]
	v_cvt_f32_f16_e32 v24, v31
	v_cvt_f32_f16_sdwa v25, v31 dst_sel:DWORD dst_unused:UNUSED_PAD src0_sel:WORD_1
	v_cvt_f32_f16_e32 v28, v35
	v_cvt_f32_f16_sdwa v29, v35 dst_sel:DWORD dst_unused:UNUSED_PAD src0_sel:WORD_1
	v_pk_mul_f32 v[26:27], v[26:27], v[86:87] op_sel_hi:[1,0]
	v_pk_fma_f32 v[22:23], v[40:41], v[22:23], v[158:159]
	v_pk_fma_f32 v[26:27], v[42:43], v[26:27], v[160:161]
	v_pk_fma_f32 v[22:23], v[8:9], v[172:173], v[22:23] op_sel_hi:[0,1,1]
	v_pk_fma_f32 v[8:9], v[8:9], v[24:25], v[26:27] op_sel_hi:[0,1,1]
	v_pk_mul_f32 v[22:23], v[22:23], v[162:163]
	v_pk_mul_f32 v[8:9], v[8:9], v[28:29]
	v_cvt_pk_f16_f32 v22, v22, v23
	v_cvt_pk_f16_f32 v23, v8, v9
	v_add_u32_e32 v8, s29, v107
	v_ashrrev_i32_e32 v9, 31, v8
	v_lshlrev_b64 v[8:9], 11, v[8:9]
	v_lshl_add_u64 v[8:9], v[60:61], 0, v[8:9]
	global_store_dwordx4 v[8:9], v[20:23], off sc1
	s_nop 1
.LBB0_583:
	s_or_b64 exec, exec, s[24:25]
	s_and_b32 s22, s29, 0xc0
	s_cmpk_lg_i32 s22, 0xc0
	s_cselect_b64 s[22:23], -1, 0
	s_or_b64 s[24:25], s[36:37], s[22:23]
	s_mov_b64 s[22:23], -1
	s_and_b64 vcc, exec, s[24:25]
	s_cbranch_vccnz .LBB0_589
	s_lshr_b32 s29, s29, 2
	s_and_b32 s29, s29, 0x1fffffc0
	s_add_i32 s29, s29, s85
	s_lshl_b32 s29, s29, 2
	v_readlane_b32 s24, v255, 34
	v_readlane_b32 s25, v255, 35
	v_mov_b32_e32 v250, s29
	v_mov_b32_e32 v251, 0
	s_nop 1
	v_lshl_add_u64 v[250:251], s[24:25], 0, v[250:251]
	s_and_saveexec_b64 s[22:23], s[6:7]
	v_mov_b32_e32 v252, 1
	s_mov_b64 exec, s[22:23]
	s_branch .LBB0_590

.LBB0_594:
	s_add_u32 s50, s76, 0x1600000
	s_addc_u32 s51, s77, 0
	s_add_u32 s22, s76, 0x7a00000
	v_readlane_b32 s0, v255, 10
	s_addc_u32 s23, s77, 0
	s_lshl_b32 s60, s0, 1
	v_readlane_b32 s8, v255, 0
	s_addk_i32 s60, 0xff00
	s_lshl_b32 s52, s74, 13
	s_lshl_b32 s53, s68, 12
	v_readlane_b32 s9, v255, 1
	v_readlane_b32 s10, v255, 2
	v_readlane_b32 s11, v255, 3
	v_readlane_b32 s12, v255, 4
	v_readlane_b32 s13, v255, 5
	s_cmp_eq_u32 s74, 1
	v_readlane_b32 s14, v255, 6
	v_readlane_b32 s15, v255, 7
	s_mov_b64 s[8:9], s[12:13]
	s_cselect_b64 s[4:5], -1, 0
	s_lshl_b32 s54, s68, 6
	s_lshl_b32 s55, s74, 17
	s_mov_b64 s[10:11], s[14:15]
	s_add_u32 s24, s10, 0x4000000
	s_addc_u32 s25, s11, 0
	s_add_u32 s56, s76, 0x18000
	s_waitcnt vmcnt(0)
	s_addc_u32 s57, s77, 0
	v_readlane_b32 s72, v255, 34
	s_cmpk_gt_i32 s2, 0x7f
	v_readlane_b32 s97, v255, 32
	v_readlane_b32 s73, v255, 35
	s_waitcnt vmcnt(0) lgkmcnt(0)
	s_barrier
	v_cmp_ne_u32_e32 vcc, 0, v252
	s_cbranch_vccz .Lpub_none2
	s_mov_b64 exec, vcc
	global_atomic_add v[250:251], v252, off
	s_mov_b64 exec, -1
	s_nop 1
	v_mov_b32_e32 v252, 0
.Lpub_none2:
	s_cbranch_scc1 .LBB0_650
	s_add_u32 s3, s76, 0x13d40080
	s_addc_u32 s28, s77, 0
	s_add_u32 s29, s76, 0x1600100
	s_addc_u32 s33, s77, 0
	s_add_i32 s63, 0, 0x27e40
	s_mov_b32 s1, 0
	v_mov_b32_e32 v129, 0
	s_movk_i32 s61, 0x200
	s_movk_i32 s62, 0x70
	s_mov_b32 s69, 0x1fffe0
	s_mov_b64 s[6:7], 0x80
	s_mov_b64 s[8:9], 0x100
	v_mov_b32_e32 v140, s63
	v_mov_b32_e32 v141, 1
	s_branch .LBB0_598
